# G2 epilogue de-serialised: gate-input loads issued one row group ahead into free fragment registers, counted waits
# baseline (speedup 1.0000x reference)
.LBB0_466:
	v_lshl_or_b32 v50, s14, 8, v183
	v_lshl_add_u32 v180, s12, 8, v1
	v_ashrrev_i32_e32 v51, 31, v50
	v_ashrrev_i32_e32 v181, 31, v180
	v_lshlrev_b64 v[52:53], 2, v[50:51]
	v_lshlrev_b64 v[54:55], 11, v[180:181]
	v_lshl_add_u64 v[58:59], s[82:83], 0, v[52:53]
	v_lshlrev_b64 v[178:179], 1, v[50:51]
	v_lshl_add_u64 v[50:51], s[8:9], 0, v[54:55]
	global_load_dwordx4 v[70:73], v[58:59], off
	global_load_dwordx4 v[66:69], v[58:59], off offset:16
	v_lshl_add_u64 v[198:199], v[50:51], 0, v[178:179]
	global_load_dwordx4 v[74:77], v[58:59], off offset:512
	global_load_dwordx4 v[194:197], v[198:199], off
	v_lshl_add_u64 v[62:63], s[86:87], 0, v[52:53]
	global_load_dwordx4 v[54:57], v[62:63], off
	global_load_dwordx4 v[50:53], v[62:63], off offset:16
	global_load_dwordx4 v[78:81], v[58:59], off offset:528
	v_and_b32_e32 v59, 64, v187
	v_xor_b32_e32 v58, 16, v187
	v_add_u32_e32 v59, 64, v59
	v_xor_b32_e32 v60, 32, v187
	v_cmp_lt_i32_e32 vcc, v58, v59
	s_waitcnt vmcnt(0)
	v_pk_add_f32 v[160:161], v[160:161], v[72:73]
	v_cndmask_b32_e32 v61, v187, v58, vcc
	v_cmp_lt_i32_e32 vcc, v60, v59
	v_lshlrev_b64 v[58:59], 12, v[180:181]
	v_lshl_add_u64 v[200:201], s[16:17], 0, v[58:59]
	v_cndmask_b32_e32 v60, v187, v60, vcc
	v_lshlrev_b32_e32 v189, 2, v61
	v_lshlrev_b32_e32 v188, 2, v60
	global_load_dwordx4 v[58:61], v[62:63], off offset:528
	s_nop 0
	global_load_dwordx4 v[62:65], v[62:63], off offset:512
	v_lshl_add_u64 v[202:203], v[200:201], 0, v[178:179]
	global_load_dwordx4 v[198:201], v[198:199], off offset:256
	v_add_u32_e32 v226, 16, v180
	v_ashrrev_i32_e32 v227, 31, v226
	v_lshlrev_b64 v[228:229], 11, v[226:227]
	v_lshl_add_u64 v[228:229], s[8:9], 0, v[228:229]
	v_lshl_add_u64 v[228:229], v[228:229], 0, v[178:179]
	global_load_dwordx4 v[218:221], v[228:229], off
	global_load_dwordx4 v[222:225], v[228:229], off offset:256
	v_pk_add_f32 v[158:159], v[158:159], v[70:71]
	v_pk_add_f32 v[156:157], v[156:157], v[68:69]
	v_pk_add_f32 v[154:155], v[154:155], v[66:67]
	v_pk_add_f32 v[204:205], v[152:153], v[76:77]
	v_pk_add_f32 v[206:207], v[150:151], v[74:75]
	v_mul_f32_e32 v158, 0xbfb8aa3b, v158
	v_mul_f32_e32 v193, 0xbfb8aa3b, v154
	v_mul_f32_e32 v159, 0xbfb8aa3b, v159
	v_lshlrev_b32_e32 v150, 16, v194
	v_and_b32_e32 v151, 0xffff0000, v194
	v_mul_f32_e32 v194, 0xbfb8aa3b, v155
	v_lshlrev_b32_e32 v152, 16, v196
	v_and_b32_e32 v153, 0xffff0000, v196
	v_mul_f32_e32 v160, 0xbfb8aa3b, v160
	v_mul_f32_e32 v196, 0xbfb8aa3b, v156
	v_mul_f32_e32 v161, 0xbfb8aa3b, v161
	v_lshlrev_b32_e32 v154, 16, v195
	v_and_b32_e32 v155, 0xffff0000, v195
	v_mul_f32_e32 v195, 0xbfb8aa3b, v157
	v_exp_f32_e32 v158, v158
	v_exp_f32_e32 v193, v193
	v_exp_f32_e32 v159, v159
	v_exp_f32_e32 v194, v194
	v_exp_f32_e32 v160, v160
	v_exp_f32_e32 v196, v196
	v_exp_f32_e32 v161, v161
	v_exp_f32_e32 v195, v195
	v_lshlrev_b32_e32 v156, 16, v197
	v_and_b32_e32 v157, 0xffff0000, v197
	v_mul_f32_e32 v197, 0xbfb8aa3b, v206
	v_exp_f32_e32 v206, v197
	v_add_f32_e32 v158, 1.0, v158
	v_add_f32_e32 v193, 1.0, v193
	v_add_f32_e32 v159, 1.0, v159
	v_add_f32_e32 v194, 1.0, v194
	v_add_f32_e32 v197, 1.0, v160
	v_add_f32_e32 v196, 1.0, v196
	v_add_f32_e32 v208, 1.0, v161
	v_add_f32_e32 v209, 1.0, v195
	v_rcp_f32_e32 v158, v158
	v_rcp_f32_e32 v160, v193
	v_rcp_f32_e32 v159, v159
	v_rcp_f32_e32 v161, v194
	v_rcp_f32_e32 v194, v197
	v_rcp_f32_e32 v196, v196
	v_rcp_f32_e32 v195, v208
	v_rcp_f32_e32 v197, v209
	v_pk_mul_f32 v[150:151], v[158:159], v[150:151]
	v_pk_mul_f32 v[152:153], v[160:161], v[152:153]
	v_pk_mul_f32 v[154:155], v[194:195], v[154:155]
	v_pk_mul_f32 v[156:157], v[196:197], v[156:157]
	v_pk_mul_f32 v[158:159], v[150:151], v[150:151]
	v_pk_mul_f32 v[160:161], v[154:155], v[154:155]
	v_pk_mul_f32 v[194:195], v[152:153], v[152:153]
	v_pk_mul_f32 v[196:197], v[156:157], v[156:157]
	v_pk_mul_f32 v[154:155], v[56:57], v[154:155]
	v_pk_mul_f32 v[150:151], v[54:55], v[150:151]
	v_pk_mul_f32 v[156:157], v[52:53], v[156:157]
	v_pk_mul_f32 v[152:153], v[50:51], v[152:153]
	v_cvt_pk_bf16_f32 v150, v150, v151
	v_cvt_pk_bf16_f32 v151, v154, v155
	v_cvt_pk_bf16_f32 v152, v152, v153
	v_cvt_pk_bf16_f32 v153, v156, v157
	global_store_dwordx4 v[202:203], v[150:153], off
	v_pk_add_f32 v[146:147], v[146:147], v[78:79]
	v_pk_add_f32 v[148:149], v[148:149], v[80:81]
	v_mul_f32_e32 v151, 0xbfb8aa3b, v207
	v_exp_f32_e32 v151, v151
	v_mul_f32_e32 v146, 0xbfb8aa3b, v146
	v_mul_f32_e32 v147, 0xbfb8aa3b, v147
	v_add_f32_e32 v150, 1.0, v206
	v_exp_f32_e32 v146, v146
	v_add_f32_e32 v151, 1.0, v151
	v_exp_f32_e32 v147, v147
	v_rcp_f32_e32 v150, v150
	v_rcp_f32_e32 v151, v151
	v_add_f32_e32 v146, 1.0, v146
	v_add_f32_e32 v147, 1.0, v147
	v_rcp_f32_e32 v146, v146
	s_waitcnt vmcnt(3)
	v_lshlrev_b32_e32 v152, 16, v198
	v_and_b32_e32 v153, 0xffff0000, v198
	v_pk_mul_f32 v[150:151], v[150:151], v[152:153]
	v_rcp_f32_e32 v147, v147
	v_mul_f32_e32 v152, 0xbfb8aa3b, v204
	v_exp_f32_e32 v154, v152
	v_lshlrev_b32_e32 v152, 16, v200
	v_and_b32_e32 v153, 0xffff0000, v200
	v_mul_f32_e32 v148, 0xbfb8aa3b, v148
	v_pk_mul_f32 v[146:147], v[146:147], v[152:153]
	v_exp_f32_e32 v153, v148
	v_mul_f32_e32 v148, 0xbfb8aa3b, v205
	v_add_f32_e32 v152, 1.0, v154
	v_exp_f32_e32 v154, v148
	v_mul_f32_e32 v149, 0xbfb8aa3b, v149
	v_exp_f32_e32 v156, v149
	v_rcp_f32_e32 v148, v152
	v_add_f32_e32 v152, 1.0, v153
	v_add_f32_e32 v153, 1.0, v154
	v_rcp_f32_e32 v149, v153
	v_add_f32_e32 v153, 1.0, v156
	v_rcp_f32_e32 v152, v152
	v_rcp_f32_e32 v153, v153
	v_lshlrev_b32_e32 v154, 16, v199
	v_and_b32_e32 v155, 0xffff0000, v199
	v_pk_mul_f32 v[148:149], v[148:149], v[154:155]
	v_lshlrev_b32_e32 v154, 16, v201
	v_and_b32_e32 v155, 0xffff0000, v201
	v_pk_mul_f32 v[152:153], v[152:153], v[154:155]
	v_pk_mul_f32 v[154:155], v[150:151], v[150:151]
	v_pk_mul_f32 v[156:157], v[148:149], v[148:149]
	v_add_f32_e32 v154, v154, v155
	v_add_f32_e32 v156, v156, v157
	v_pk_mul_f32 v[198:199], v[146:147], v[146:147]
	v_add_f32_e32 v154, v154, v156
	v_add_f32_e32 v156, v160, v161
	v_add_f32_e32 v157, v158, v159
	v_pk_mul_f32 v[200:201], v[152:153], v[152:153]
	v_add_f32_e32 v155, v198, v199
	v_add_f32_e32 v156, v157, v156
	v_add_f32_e32 v157, v194, v195
	v_add_f32_e32 v193, v200, v201
	v_add_f32_e32 v154, v155, v154
	v_add_f32_e32 v155, v196, v197
	v_add_f32_e32 v156, v157, v156
	v_add_f32_e32 v154, v193, v154
	v_add_f32_e32 v155, v155, v156
	v_add_f32_e32 v156, v155, v154
	ds_bpermute_b32 v157, v189, v156
	v_pk_mul_f32 v[154:155], v[64:65], v[148:149]
	v_pk_mul_f32 v[148:149], v[62:63], v[150:151]
	v_pk_mul_f32 v[150:151], v[58:59], v[146:147]
	v_pk_mul_f32 v[152:153], v[60:61], v[152:153]
	s_waitcnt lgkmcnt(0)
	v_add_f32_e32 v146, v156, v157
	ds_bpermute_b32 v147, v188, v146
	v_cvt_pk_bf16_f32 v148, v148, v149
	v_cvt_pk_bf16_f32 v149, v154, v155
	v_cvt_pk_bf16_f32 v150, v150, v151
	v_cvt_pk_bf16_f32 v151, v152, v153
	global_store_dwordx4 v[202:203], v[148:151], off offset:256
	s_and_saveexec_b64 s[12:13], s[4:5]
	s_cbranch_execz .LBB0_468
	v_lshl_add_u64 v[148:149], v[180:181], 2, s[18:19]
	s_waitcnt lgkmcnt(0)
	v_add_f32_e32 v146, v146, v147
	global_atomic_add_f32 v[148:149], v146, off
.LBB0_468:
	s_or_b64 exec, exec, s[12:13]
	v_or_b32_e32 v146, 16, v180
	s_waitcnt lgkmcnt(0)
	v_ashrrev_i32_e32 v147, 31, v146
	v_lshlrev_b64 v[148:149], 11, v[146:147]
	v_lshl_add_u64 v[148:149], s[8:9], 0, v[148:149]
	v_lshl_add_u64 v[152:153], v[148:149], 0, v[178:179]
	v_add_u32_e32 v226, 32, v180
	v_ashrrev_i32_e32 v227, 31, v226
	v_lshlrev_b64 v[228:229], 11, v[226:227]
	v_lshl_add_u64 v[228:229], s[8:9], 0, v[228:229]
	v_lshl_add_u64 v[228:229], v[228:229], 0, v[178:179]
	global_load_dwordx4 v[210:213], v[228:229], off
	global_load_dwordx4 v[214:217], v[228:229], off offset:256
	v_pk_add_f32 v[144:145], v[144:145], v[72:73]
	v_pk_add_f32 v[142:143], v[142:143], v[70:71]
	v_pk_add_f32 v[140:141], v[140:141], v[68:69]
	v_pk_add_f32 v[138:139], v[138:139], v[66:67]
	v_pk_add_f32 v[134:135], v[134:135], v[74:75]
	v_pk_add_f32 v[156:157], v[132:133], v[80:81]
	v_mul_f32_e32 v132, 0xbfb8aa3b, v142
	v_mul_f32_e32 v133, 0xbfb8aa3b, v138
	v_mul_f32_e32 v138, 0xbfb8aa3b, v143
	v_mul_f32_e32 v139, 0xbfb8aa3b, v139
	v_mul_f32_e32 v142, 0xbfb8aa3b, v144
	v_mul_f32_e32 v140, 0xbfb8aa3b, v140
	v_mul_f32_e32 v143, 0xbfb8aa3b, v145
	v_mul_f32_e32 v141, 0xbfb8aa3b, v141
	v_mul_f32_e32 v134, 0xbfb8aa3b, v134
	v_mul_f32_e32 v135, 0xbfb8aa3b, v135
	v_exp_f32_e32 v132, v132
	v_exp_f32_e32 v133, v133
	v_exp_f32_e32 v158, v138
	v_exp_f32_e32 v159, v139
	v_exp_f32_e32 v142, v142
	v_exp_f32_e32 v140, v140
	v_exp_f32_e32 v143, v143
	v_exp_f32_e32 v141, v141
	v_pk_add_f32 v[130:131], v[130:131], v[78:79]
	v_exp_f32_e32 v134, v134
	v_exp_f32_e32 v135, v135
	v_mul_f32_e32 v144, 0xbfb8aa3b, v130
	v_mul_f32_e32 v145, 0xbfb8aa3b, v131
	v_lshlrev_b64 v[130:131], 12, v[146:147]
	v_lshl_add_u64 v[130:131], s[16:17], 0, v[130:131]
	v_lshl_add_u64 v[138:139], v[130:131], 0, v[178:179]
	v_add_f32_e32 v130, 1.0, v132
	v_add_f32_e32 v131, 1.0, v133
	v_add_f32_e32 v133, 1.0, v158
	v_add_f32_e32 v158, 1.0, v159
	v_add_f32_e32 v142, 1.0, v142
	v_add_f32_e32 v140, 1.0, v140
	v_add_f32_e32 v143, 1.0, v143
	v_add_f32_e32 v141, 1.0, v141
	v_add_f32_e32 v159, 1.0, v134
	v_add_f32_e32 v160, 1.0, v135
	v_rcp_f32_e32 v130, v130
	v_rcp_f32_e32 v132, v131
	v_rcp_f32_e32 v131, v133
	v_rcp_f32_e32 v133, v158
	v_rcp_f32_e32 v134, v142
	v_rcp_f32_e32 v140, v140
	v_rcp_f32_e32 v135, v143
	v_rcp_f32_e32 v141, v141
	v_exp_f32_e32 v145, v145
	v_rcp_f32_e32 v142, v159
	v_rcp_f32_e32 v143, v160
	v_pk_add_f32 v[136:137], v[136:137], v[76:77]
	v_exp_f32_e32 v144, v144
	s_waitcnt vmcnt(5)
	v_lshlrev_b32_e32 v158, 16, v218
	v_and_b32_e32 v159, 0xffff0000, v218
	v_lshlrev_b32_e32 v160, 16, v220
	v_and_b32_e32 v161, 0xffff0000, v220
	v_lshlrev_b32_e32 v148, 16, v219
	v_and_b32_e32 v149, 0xffff0000, v219
	v_lshlrev_b32_e32 v150, 16, v221
	v_and_b32_e32 v151, 0xffff0000, v221
	v_pk_mul_f32 v[130:131], v[130:131], v[158:159]
	v_pk_mul_f32 v[132:133], v[132:133], v[160:161]
	v_pk_mul_f32 v[134:135], v[134:135], v[148:149]
	v_pk_mul_f32 v[140:141], v[140:141], v[150:151]
	v_pk_mul_f32 v[148:149], v[130:131], v[130:131]
	v_pk_mul_f32 v[150:151], v[134:135], v[134:135]
	v_pk_mul_f32 v[158:159], v[132:133], v[132:133]
	v_pk_mul_f32 v[160:161], v[140:141], v[140:141]
	v_pk_mul_f32 v[134:135], v[56:57], v[134:135]
	v_pk_mul_f32 v[130:131], v[54:55], v[130:131]
	v_pk_mul_f32 v[140:141], v[52:53], v[140:141]
	v_pk_mul_f32 v[132:133], v[50:51], v[132:133]
	v_cvt_pk_bf16_f32 v130, v130, v131
	v_cvt_pk_bf16_f32 v131, v134, v135
	v_cvt_pk_bf16_f32 v132, v132, v133
	v_cvt_pk_bf16_f32 v133, v140, v141
	global_store_dwordx4 v[138:139], v[130:133], off
	v_mul_f32_e32 v135, 0xbfb8aa3b, v156
	v_exp_f32_e32 v135, v135
	v_add_f32_e32 v132, 1.0, v145
	v_rcp_f32_e32 v145, v132
	v_mul_f32_e32 v132, 0xbfb8aa3b, v136
	v_mul_f32_e32 v136, 0xbfb8aa3b, v137
	v_exp_f32_e32 v137, v136
	v_add_f32_e32 v135, 1.0, v135
	v_exp_f32_e32 v134, v132
	v_rcp_f32_e32 v136, v135
	v_add_f32_e32 v135, 1.0, v137
	v_mul_f32_e32 v137, 0xbfb8aa3b, v157
	v_exp_f32_e32 v137, v137
	v_add_f32_e32 v134, 1.0, v134
	v_rcp_f32_e32 v134, v134
	v_rcp_f32_e32 v135, v135
	v_add_f32_e32 v137, 1.0, v137
	v_add_f32_e32 v144, 1.0, v144
	v_rcp_f32_e32 v137, v137
	v_rcp_f32_e32 v144, v144
	s_waitcnt vmcnt(5)
	v_lshlrev_b32_e32 v194, 16, v222
	v_and_b32_e32 v195, 0xffff0000, v222
	v_lshlrev_b32_e32 v140, 16, v223
	v_and_b32_e32 v141, 0xffff0000, v223
	v_pk_mul_f32 v[130:131], v[142:143], v[194:195]
	v_pk_mul_f32 v[134:135], v[134:135], v[140:141]
	v_lshlrev_b32_e32 v140, 16, v225
	v_and_b32_e32 v141, 0xffff0000, v225
	v_lshlrev_b32_e32 v132, 16, v224
	v_and_b32_e32 v133, 0xffff0000, v224
	v_pk_mul_f32 v[136:137], v[136:137], v[140:141]
	v_pk_mul_f32 v[140:141], v[130:131], v[130:131]
	v_pk_mul_f32 v[142:143], v[134:135], v[134:135]
	v_pk_mul_f32 v[132:133], v[144:145], v[132:133]
	v_add_f32_e32 v142, v142, v143
	v_add_f32_e32 v140, v140, v141
	v_pk_mul_f32 v[144:145], v[132:133], v[132:133]
	v_add_f32_e32 v140, v140, v142
	v_add_f32_e32 v142, v150, v151
	v_add_f32_e32 v143, v148, v149
	v_pk_mul_f32 v[152:153], v[136:137], v[136:137]
	v_add_f32_e32 v141, v144, v145
	v_add_f32_e32 v142, v143, v142
	v_add_f32_e32 v143, v158, v159
	v_add_f32_e32 v152, v152, v153
	v_add_f32_e32 v140, v141, v140
	v_add_f32_e32 v141, v160, v161
	v_add_f32_e32 v142, v143, v142
	v_add_f32_e32 v140, v152, v140
	v_add_f32_e32 v141, v141, v142
	v_add_f32_e32 v142, v141, v140
	ds_bpermute_b32 v143, v189, v142
	v_pk_mul_f32 v[130:131], v[62:63], v[130:131]
	v_pk_mul_f32 v[140:141], v[58:59], v[132:133]
	v_cvt_pk_bf16_f32 v132, v130, v131
	v_pk_mul_f32 v[134:135], v[64:65], v[134:135]
	s_waitcnt lgkmcnt(0)
	v_add_f32_e32 v130, v142, v143
	ds_bpermute_b32 v131, v188, v130
	v_pk_mul_f32 v[136:137], v[60:61], v[136:137]
	v_cvt_pk_bf16_f32 v133, v134, v135
	v_cvt_pk_bf16_f32 v134, v140, v141
	v_cvt_pk_bf16_f32 v135, v136, v137
	global_store_dwordx4 v[138:139], v[132:135], off offset:256
	s_and_saveexec_b64 s[12:13], s[4:5]
	s_cbranch_execz .LBB0_470
	v_lshl_add_u64 v[132:133], v[146:147], 2, s[18:19]
	s_waitcnt lgkmcnt(0)
	v_add_f32_e32 v130, v130, v131
	global_atomic_add_f32 v[132:133], v130, off
.LBB0_470:
	s_or_b64 exec, exec, s[12:13]
	v_or_b32_e32 v130, 32, v180
	s_waitcnt lgkmcnt(0)
	v_ashrrev_i32_e32 v131, 31, v130
	v_lshlrev_b64 v[132:133], 11, v[130:131]
	v_lshl_add_u64 v[132:133], s[8:9], 0, v[132:133]
	v_lshl_add_u64 v[136:137], v[132:133], 0, v[178:179]
	v_add_u32_e32 v226, 48, v180
	v_ashrrev_i32_e32 v227, 31, v226
	v_lshlrev_b64 v[228:229], 11, v[226:227]
	v_lshl_add_u64 v[228:229], s[8:9], 0, v[228:229]
	v_lshl_add_u64 v[228:229], v[228:229], 0, v[178:179]
	global_load_dwordx4 v[218:221], v[228:229], off
	global_load_dwordx4 v[222:225], v[228:229], off offset:256
	v_pk_add_f32 v[128:129], v[128:129], v[72:73]
	v_pk_add_f32 v[126:127], v[126:127], v[70:71]
	v_pk_add_f32 v[124:125], v[124:125], v[68:69]
	v_pk_add_f32 v[122:123], v[122:123], v[66:67]
	v_pk_add_f32 v[118:119], v[118:119], v[74:75]
	v_pk_add_f32 v[140:141], v[116:117], v[80:81]
	v_mul_f32_e32 v116, 0xbfb8aa3b, v126
	v_mul_f32_e32 v117, 0xbfb8aa3b, v122
	v_mul_f32_e32 v122, 0xbfb8aa3b, v127
	v_mul_f32_e32 v123, 0xbfb8aa3b, v123
	v_mul_f32_e32 v126, 0xbfb8aa3b, v128
	v_mul_f32_e32 v124, 0xbfb8aa3b, v124
	v_mul_f32_e32 v127, 0xbfb8aa3b, v129
	v_mul_f32_e32 v125, 0xbfb8aa3b, v125
	v_mul_f32_e32 v118, 0xbfb8aa3b, v118
	v_mul_f32_e32 v119, 0xbfb8aa3b, v119
	v_exp_f32_e32 v116, v116
	v_exp_f32_e32 v117, v117
	v_exp_f32_e32 v142, v122
	v_exp_f32_e32 v143, v123
	v_exp_f32_e32 v126, v126
	v_exp_f32_e32 v124, v124
	v_exp_f32_e32 v127, v127
	v_exp_f32_e32 v125, v125
	v_pk_add_f32 v[114:115], v[114:115], v[78:79]
	v_exp_f32_e32 v118, v118
	v_exp_f32_e32 v119, v119
	v_mul_f32_e32 v128, 0xbfb8aa3b, v114
	v_mul_f32_e32 v129, 0xbfb8aa3b, v115
	v_lshlrev_b64 v[114:115], 12, v[130:131]
	v_lshl_add_u64 v[114:115], s[16:17], 0, v[114:115]
	v_lshl_add_u64 v[122:123], v[114:115], 0, v[178:179]
	v_add_f32_e32 v114, 1.0, v116
	v_add_f32_e32 v115, 1.0, v117
	v_add_f32_e32 v117, 1.0, v142
	v_add_f32_e32 v142, 1.0, v143
	v_add_f32_e32 v126, 1.0, v126
	v_add_f32_e32 v124, 1.0, v124
	v_add_f32_e32 v127, 1.0, v127
	v_add_f32_e32 v125, 1.0, v125
	v_add_f32_e32 v143, 1.0, v118
	v_add_f32_e32 v144, 1.0, v119
	v_rcp_f32_e32 v114, v114
	v_rcp_f32_e32 v116, v115
	v_rcp_f32_e32 v115, v117
	v_rcp_f32_e32 v117, v142
	v_rcp_f32_e32 v118, v126
	v_rcp_f32_e32 v124, v124
	v_rcp_f32_e32 v119, v127
	v_rcp_f32_e32 v125, v125
	v_exp_f32_e32 v129, v129
	v_rcp_f32_e32 v126, v143
	v_rcp_f32_e32 v127, v144
	v_pk_add_f32 v[120:121], v[120:121], v[76:77]
	v_exp_f32_e32 v128, v128
	s_waitcnt vmcnt(5)
	v_lshlrev_b32_e32 v142, 16, v210
	v_and_b32_e32 v143, 0xffff0000, v210
	v_lshlrev_b32_e32 v144, 16, v212
	v_and_b32_e32 v145, 0xffff0000, v212
	v_lshlrev_b32_e32 v132, 16, v211
	v_and_b32_e32 v133, 0xffff0000, v211
	v_lshlrev_b32_e32 v134, 16, v213
	v_and_b32_e32 v135, 0xffff0000, v213
	v_pk_mul_f32 v[114:115], v[114:115], v[142:143]
	v_pk_mul_f32 v[116:117], v[116:117], v[144:145]
	v_pk_mul_f32 v[118:119], v[118:119], v[132:133]
	v_pk_mul_f32 v[124:125], v[124:125], v[134:135]
	v_pk_mul_f32 v[132:133], v[114:115], v[114:115]
	v_pk_mul_f32 v[134:135], v[118:119], v[118:119]
	v_pk_mul_f32 v[142:143], v[116:117], v[116:117]
	v_pk_mul_f32 v[144:145], v[124:125], v[124:125]
	v_pk_mul_f32 v[118:119], v[56:57], v[118:119]
	v_pk_mul_f32 v[114:115], v[54:55], v[114:115]
	v_pk_mul_f32 v[124:125], v[52:53], v[124:125]
	v_pk_mul_f32 v[116:117], v[50:51], v[116:117]
	v_cvt_pk_bf16_f32 v114, v114, v115
	v_cvt_pk_bf16_f32 v115, v118, v119
	v_cvt_pk_bf16_f32 v116, v116, v117
	v_cvt_pk_bf16_f32 v117, v124, v125
	global_store_dwordx4 v[122:123], v[114:117], off
	v_mul_f32_e32 v119, 0xbfb8aa3b, v140
	v_exp_f32_e32 v119, v119
	v_add_f32_e32 v116, 1.0, v129
	v_rcp_f32_e32 v129, v116
	v_mul_f32_e32 v116, 0xbfb8aa3b, v120
	v_mul_f32_e32 v120, 0xbfb8aa3b, v121
	v_exp_f32_e32 v121, v120
	v_add_f32_e32 v119, 1.0, v119
	v_exp_f32_e32 v118, v116
	v_rcp_f32_e32 v120, v119
	v_add_f32_e32 v119, 1.0, v121
	v_mul_f32_e32 v121, 0xbfb8aa3b, v141
	v_exp_f32_e32 v121, v121
	v_add_f32_e32 v118, 1.0, v118
	v_rcp_f32_e32 v118, v118
	v_rcp_f32_e32 v119, v119
	v_add_f32_e32 v121, 1.0, v121
	v_add_f32_e32 v128, 1.0, v128
	v_rcp_f32_e32 v121, v121
	v_rcp_f32_e32 v128, v128
	s_waitcnt vmcnt(5)
	v_lshlrev_b32_e32 v146, 16, v214
	v_and_b32_e32 v147, 0xffff0000, v214
	v_lshlrev_b32_e32 v124, 16, v215
	v_and_b32_e32 v125, 0xffff0000, v215
	v_pk_mul_f32 v[114:115], v[126:127], v[146:147]
	v_pk_mul_f32 v[118:119], v[118:119], v[124:125]
	v_lshlrev_b32_e32 v124, 16, v217
	v_and_b32_e32 v125, 0xffff0000, v217
	v_lshlrev_b32_e32 v116, 16, v216
	v_and_b32_e32 v117, 0xffff0000, v216
	v_pk_mul_f32 v[120:121], v[120:121], v[124:125]
	v_pk_mul_f32 v[124:125], v[114:115], v[114:115]
	v_pk_mul_f32 v[126:127], v[118:119], v[118:119]
	v_pk_mul_f32 v[116:117], v[128:129], v[116:117]
	v_add_f32_e32 v126, v126, v127
	v_add_f32_e32 v124, v124, v125
	v_pk_mul_f32 v[128:129], v[116:117], v[116:117]
	v_add_f32_e32 v124, v124, v126
	v_add_f32_e32 v126, v134, v135
	v_add_f32_e32 v127, v132, v133
	v_pk_mul_f32 v[136:137], v[120:121], v[120:121]
	v_add_f32_e32 v125, v128, v129
	v_add_f32_e32 v126, v127, v126
	v_add_f32_e32 v127, v142, v143
	v_add_f32_e32 v136, v136, v137
	v_add_f32_e32 v124, v125, v124
	v_add_f32_e32 v125, v144, v145
	v_add_f32_e32 v126, v127, v126
	v_add_f32_e32 v124, v136, v124
	v_add_f32_e32 v125, v125, v126
	v_add_f32_e32 v126, v125, v124
	ds_bpermute_b32 v127, v189, v126
	v_pk_mul_f32 v[114:115], v[62:63], v[114:115]
	v_pk_mul_f32 v[124:125], v[58:59], v[116:117]
	v_cvt_pk_bf16_f32 v116, v114, v115
	v_pk_mul_f32 v[118:119], v[64:65], v[118:119]
	s_waitcnt lgkmcnt(0)
	v_add_f32_e32 v114, v126, v127
	ds_bpermute_b32 v115, v188, v114
	v_pk_mul_f32 v[120:121], v[60:61], v[120:121]
	v_cvt_pk_bf16_f32 v117, v118, v119
	v_cvt_pk_bf16_f32 v118, v124, v125
	v_cvt_pk_bf16_f32 v119, v120, v121
	global_store_dwordx4 v[122:123], v[116:119], off offset:256
	s_and_saveexec_b64 s[12:13], s[4:5]
	s_cbranch_execz .LBB0_472
	v_lshl_add_u64 v[116:117], v[130:131], 2, s[18:19]
	s_waitcnt lgkmcnt(0)
	v_add_f32_e32 v114, v114, v115
	global_atomic_add_f32 v[116:117], v114, off
.LBB0_472:
	s_or_b64 exec, exec, s[12:13]
	v_or_b32_e32 v114, 48, v180
	s_waitcnt lgkmcnt(0)
	v_ashrrev_i32_e32 v115, 31, v114
	v_lshlrev_b64 v[116:117], 11, v[114:115]
	v_lshl_add_u64 v[116:117], s[8:9], 0, v[116:117]
	v_lshl_add_u64 v[120:121], v[116:117], 0, v[178:179]
	v_add_u32_e32 v226, 128, v180
	v_ashrrev_i32_e32 v227, 31, v226
	v_lshlrev_b64 v[228:229], 11, v[226:227]
	v_lshl_add_u64 v[228:229], s[8:9], 0, v[228:229]
	v_lshl_add_u64 v[228:229], v[228:229], 0, v[178:179]
	global_load_dwordx4 v[210:213], v[228:229], off
	global_load_dwordx4 v[214:217], v[228:229], off offset:256
	v_pk_add_f32 v[112:113], v[112:113], v[72:73]
	v_pk_add_f32 v[110:111], v[110:111], v[70:71]
	v_pk_add_f32 v[108:109], v[108:109], v[68:69]
	v_pk_add_f32 v[106:107], v[106:107], v[66:67]
	v_pk_add_f32 v[102:103], v[102:103], v[74:75]
	v_pk_add_f32 v[124:125], v[100:101], v[80:81]
	v_mul_f32_e32 v100, 0xbfb8aa3b, v110
	v_mul_f32_e32 v101, 0xbfb8aa3b, v106
	v_mul_f32_e32 v106, 0xbfb8aa3b, v111
	v_mul_f32_e32 v107, 0xbfb8aa3b, v107
	v_mul_f32_e32 v110, 0xbfb8aa3b, v112
	v_mul_f32_e32 v108, 0xbfb8aa3b, v108
	v_mul_f32_e32 v111, 0xbfb8aa3b, v113
	v_mul_f32_e32 v109, 0xbfb8aa3b, v109
	v_mul_f32_e32 v102, 0xbfb8aa3b, v102
	v_mul_f32_e32 v103, 0xbfb8aa3b, v103
	v_exp_f32_e32 v100, v100
	v_exp_f32_e32 v101, v101
	v_exp_f32_e32 v126, v106
	v_exp_f32_e32 v127, v107
	v_exp_f32_e32 v110, v110
	v_exp_f32_e32 v108, v108
	v_exp_f32_e32 v111, v111
	v_exp_f32_e32 v109, v109
	v_pk_add_f32 v[98:99], v[98:99], v[78:79]
	v_exp_f32_e32 v102, v102
	v_exp_f32_e32 v103, v103
	v_mul_f32_e32 v112, 0xbfb8aa3b, v98
	v_mul_f32_e32 v113, 0xbfb8aa3b, v99
	v_lshlrev_b64 v[98:99], 12, v[114:115]
	v_lshl_add_u64 v[98:99], s[16:17], 0, v[98:99]
	v_lshl_add_u64 v[106:107], v[98:99], 0, v[178:179]
	v_add_f32_e32 v98, 1.0, v100
	v_add_f32_e32 v99, 1.0, v101
	v_add_f32_e32 v101, 1.0, v126
	v_add_f32_e32 v126, 1.0, v127
	v_add_f32_e32 v110, 1.0, v110
	v_add_f32_e32 v108, 1.0, v108
	v_add_f32_e32 v111, 1.0, v111
	v_add_f32_e32 v109, 1.0, v109
	v_add_f32_e32 v127, 1.0, v102
	v_add_f32_e32 v128, 1.0, v103
	v_rcp_f32_e32 v98, v98
	v_rcp_f32_e32 v100, v99
	v_rcp_f32_e32 v99, v101
	v_rcp_f32_e32 v101, v126
	v_rcp_f32_e32 v102, v110
	v_rcp_f32_e32 v108, v108
	v_rcp_f32_e32 v103, v111
	v_rcp_f32_e32 v109, v109
	v_exp_f32_e32 v113, v113
	v_rcp_f32_e32 v110, v127
	v_rcp_f32_e32 v111, v128
	v_pk_add_f32 v[104:105], v[104:105], v[76:77]
	v_exp_f32_e32 v112, v112
	s_waitcnt vmcnt(5)
	v_lshlrev_b32_e32 v126, 16, v218
	v_and_b32_e32 v127, 0xffff0000, v218
	v_lshlrev_b32_e32 v128, 16, v220
	v_and_b32_e32 v129, 0xffff0000, v220
	v_lshlrev_b32_e32 v116, 16, v219
	v_and_b32_e32 v117, 0xffff0000, v219
	v_lshlrev_b32_e32 v118, 16, v221
	v_and_b32_e32 v119, 0xffff0000, v221
	v_pk_mul_f32 v[98:99], v[98:99], v[126:127]
	v_pk_mul_f32 v[100:101], v[100:101], v[128:129]
	v_pk_mul_f32 v[102:103], v[102:103], v[116:117]
	v_pk_mul_f32 v[108:109], v[108:109], v[118:119]
	v_pk_mul_f32 v[116:117], v[98:99], v[98:99]
	v_pk_mul_f32 v[118:119], v[102:103], v[102:103]
	v_pk_mul_f32 v[126:127], v[100:101], v[100:101]
	v_pk_mul_f32 v[128:129], v[108:109], v[108:109]
	v_pk_mul_f32 v[102:103], v[56:57], v[102:103]
	v_pk_mul_f32 v[98:99], v[54:55], v[98:99]
	v_pk_mul_f32 v[108:109], v[52:53], v[108:109]
	v_pk_mul_f32 v[100:101], v[50:51], v[100:101]
	v_cvt_pk_bf16_f32 v98, v98, v99
	v_cvt_pk_bf16_f32 v99, v102, v103
	v_cvt_pk_bf16_f32 v100, v100, v101
	v_cvt_pk_bf16_f32 v101, v108, v109
	global_store_dwordx4 v[106:107], v[98:101], off
	v_mul_f32_e32 v103, 0xbfb8aa3b, v124
	v_exp_f32_e32 v103, v103
	v_add_f32_e32 v100, 1.0, v113
	v_rcp_f32_e32 v113, v100
	v_mul_f32_e32 v100, 0xbfb8aa3b, v104
	v_mul_f32_e32 v104, 0xbfb8aa3b, v105
	v_exp_f32_e32 v105, v104
	v_add_f32_e32 v103, 1.0, v103
	v_exp_f32_e32 v102, v100
	v_rcp_f32_e32 v104, v103
	v_add_f32_e32 v103, 1.0, v105
	v_mul_f32_e32 v105, 0xbfb8aa3b, v125
	v_exp_f32_e32 v105, v105
	v_add_f32_e32 v102, 1.0, v102
	v_rcp_f32_e32 v102, v102
	v_rcp_f32_e32 v103, v103
	v_add_f32_e32 v105, 1.0, v105
	v_add_f32_e32 v112, 1.0, v112
	v_rcp_f32_e32 v105, v105
	v_rcp_f32_e32 v112, v112
	s_waitcnt vmcnt(5)
	v_lshlrev_b32_e32 v130, 16, v222
	v_and_b32_e32 v131, 0xffff0000, v222
	v_lshlrev_b32_e32 v108, 16, v223
	v_and_b32_e32 v109, 0xffff0000, v223
	v_pk_mul_f32 v[98:99], v[110:111], v[130:131]
	v_pk_mul_f32 v[102:103], v[102:103], v[108:109]
	v_lshlrev_b32_e32 v108, 16, v225
	v_and_b32_e32 v109, 0xffff0000, v225
	v_lshlrev_b32_e32 v100, 16, v224
	v_and_b32_e32 v101, 0xffff0000, v224
	v_pk_mul_f32 v[104:105], v[104:105], v[108:109]
	v_pk_mul_f32 v[108:109], v[98:99], v[98:99]
	v_pk_mul_f32 v[110:111], v[102:103], v[102:103]
	v_pk_mul_f32 v[100:101], v[112:113], v[100:101]
	v_add_f32_e32 v110, v110, v111
	v_add_f32_e32 v108, v108, v109
	v_pk_mul_f32 v[112:113], v[100:101], v[100:101]
	v_add_f32_e32 v108, v108, v110
	v_add_f32_e32 v110, v118, v119
	v_add_f32_e32 v111, v116, v117
	v_pk_mul_f32 v[120:121], v[104:105], v[104:105]
	v_add_f32_e32 v109, v112, v113
	v_add_f32_e32 v110, v111, v110
	v_add_f32_e32 v111, v126, v127
	v_add_f32_e32 v120, v120, v121
	v_add_f32_e32 v108, v109, v108
	v_add_f32_e32 v109, v128, v129
	v_add_f32_e32 v110, v111, v110
	v_add_f32_e32 v108, v120, v108
	v_add_f32_e32 v109, v109, v110
	v_add_f32_e32 v110, v109, v108
	ds_bpermute_b32 v111, v189, v110
	v_pk_mul_f32 v[98:99], v[62:63], v[98:99]
	v_pk_mul_f32 v[108:109], v[58:59], v[100:101]
	v_cvt_pk_bf16_f32 v100, v98, v99
	v_pk_mul_f32 v[102:103], v[64:65], v[102:103]
	s_waitcnt lgkmcnt(0)
	v_add_f32_e32 v98, v110, v111
	ds_bpermute_b32 v99, v188, v98
	v_pk_mul_f32 v[104:105], v[60:61], v[104:105]
	v_cvt_pk_bf16_f32 v101, v102, v103
	v_cvt_pk_bf16_f32 v102, v108, v109
	v_cvt_pk_bf16_f32 v103, v104, v105
	global_store_dwordx4 v[106:107], v[100:103], off offset:256
	s_and_saveexec_b64 s[12:13], s[4:5]
	s_cbranch_execz .LBB0_474
	v_lshl_add_u64 v[100:101], v[114:115], 2, s[18:19]
	s_waitcnt lgkmcnt(0)
	v_add_f32_e32 v98, v98, v99
	global_atomic_add_f32 v[100:101], v98, off
.LBB0_474:
	s_or_b64 exec, exec, s[12:13]
	v_add_u32_e32 v98, 0x80, v180
	s_waitcnt lgkmcnt(0)
	v_ashrrev_i32_e32 v99, 31, v98
	v_lshlrev_b64 v[100:101], 11, v[98:99]
	v_lshl_add_u64 v[100:101], s[8:9], 0, v[100:101]
	v_lshl_add_u64 v[104:105], v[100:101], 0, v[178:179]
	v_add_u32_e32 v226, 144, v180
	v_ashrrev_i32_e32 v227, 31, v226
	v_lshlrev_b64 v[228:229], 11, v[226:227]
	v_lshl_add_u64 v[228:229], s[8:9], 0, v[228:229]
	v_lshl_add_u64 v[228:229], v[228:229], 0, v[178:179]
	global_load_dwordx4 v[218:221], v[228:229], off
	global_load_dwordx4 v[222:225], v[228:229], off offset:256
	v_pk_add_f32 v[96:97], v[96:97], v[72:73]
	v_pk_add_f32 v[94:95], v[94:95], v[70:71]
	v_pk_add_f32 v[92:93], v[92:93], v[68:69]
	v_pk_add_f32 v[90:91], v[90:91], v[66:67]
	v_pk_add_f32 v[86:87], v[86:87], v[74:75]
	v_pk_add_f32 v[108:109], v[84:85], v[80:81]
	v_mul_f32_e32 v84, 0xbfb8aa3b, v94
	v_mul_f32_e32 v85, 0xbfb8aa3b, v90
	v_mul_f32_e32 v90, 0xbfb8aa3b, v95
	v_mul_f32_e32 v91, 0xbfb8aa3b, v91
	v_mul_f32_e32 v94, 0xbfb8aa3b, v96
	v_mul_f32_e32 v92, 0xbfb8aa3b, v92
	v_mul_f32_e32 v95, 0xbfb8aa3b, v97
	v_mul_f32_e32 v93, 0xbfb8aa3b, v93
	v_mul_f32_e32 v86, 0xbfb8aa3b, v86
	v_mul_f32_e32 v87, 0xbfb8aa3b, v87
	v_exp_f32_e32 v84, v84
	v_exp_f32_e32 v85, v85
	v_exp_f32_e32 v110, v90
	v_exp_f32_e32 v111, v91
	v_exp_f32_e32 v94, v94
	v_exp_f32_e32 v92, v92
	v_exp_f32_e32 v95, v95
	v_exp_f32_e32 v93, v93
	v_pk_add_f32 v[82:83], v[82:83], v[78:79]
	v_exp_f32_e32 v86, v86
	v_exp_f32_e32 v87, v87
	v_mul_f32_e32 v96, 0xbfb8aa3b, v82
	v_mul_f32_e32 v97, 0xbfb8aa3b, v83
	v_lshlrev_b64 v[82:83], 12, v[98:99]
	v_lshl_add_u64 v[82:83], s[16:17], 0, v[82:83]
	v_lshl_add_u64 v[90:91], v[82:83], 0, v[178:179]
	v_add_f32_e32 v82, 1.0, v84
	v_add_f32_e32 v83, 1.0, v85
	v_add_f32_e32 v85, 1.0, v110
	v_add_f32_e32 v110, 1.0, v111
	v_add_f32_e32 v94, 1.0, v94
	v_add_f32_e32 v92, 1.0, v92
	v_add_f32_e32 v95, 1.0, v95
	v_add_f32_e32 v93, 1.0, v93
	v_add_f32_e32 v111, 1.0, v86
	v_add_f32_e32 v112, 1.0, v87
	v_rcp_f32_e32 v82, v82
	v_rcp_f32_e32 v84, v83
	v_rcp_f32_e32 v83, v85
	v_rcp_f32_e32 v85, v110
	v_rcp_f32_e32 v86, v94
	v_rcp_f32_e32 v92, v92
	v_rcp_f32_e32 v87, v95
	v_rcp_f32_e32 v93, v93
	v_exp_f32_e32 v97, v97
	v_rcp_f32_e32 v94, v111
	v_rcp_f32_e32 v95, v112
	v_pk_add_f32 v[88:89], v[88:89], v[76:77]
	v_exp_f32_e32 v96, v96
	s_waitcnt vmcnt(5)
	v_lshlrev_b32_e32 v110, 16, v210
	v_and_b32_e32 v111, 0xffff0000, v210
	v_lshlrev_b32_e32 v112, 16, v212
	v_and_b32_e32 v113, 0xffff0000, v212
	v_lshlrev_b32_e32 v100, 16, v211
	v_and_b32_e32 v101, 0xffff0000, v211
	v_lshlrev_b32_e32 v102, 16, v213
	v_and_b32_e32 v103, 0xffff0000, v213
	v_pk_mul_f32 v[82:83], v[82:83], v[110:111]
	v_pk_mul_f32 v[84:85], v[84:85], v[112:113]
	v_pk_mul_f32 v[86:87], v[86:87], v[100:101]
	v_pk_mul_f32 v[92:93], v[92:93], v[102:103]
	v_pk_mul_f32 v[100:101], v[82:83], v[82:83]
	v_pk_mul_f32 v[102:103], v[86:87], v[86:87]
	v_pk_mul_f32 v[110:111], v[84:85], v[84:85]
	v_pk_mul_f32 v[112:113], v[92:93], v[92:93]
	v_pk_mul_f32 v[86:87], v[56:57], v[86:87]
	v_pk_mul_f32 v[82:83], v[54:55], v[82:83]
	v_pk_mul_f32 v[92:93], v[52:53], v[92:93]
	v_pk_mul_f32 v[84:85], v[50:51], v[84:85]
	v_cvt_pk_bf16_f32 v82, v82, v83
	v_cvt_pk_bf16_f32 v83, v86, v87
	v_cvt_pk_bf16_f32 v84, v84, v85
	v_cvt_pk_bf16_f32 v85, v92, v93
	global_store_dwordx4 v[90:91], v[82:85], off
	v_mul_f32_e32 v87, 0xbfb8aa3b, v108
	v_exp_f32_e32 v87, v87
	v_add_f32_e32 v84, 1.0, v97
	v_rcp_f32_e32 v97, v84
	v_mul_f32_e32 v84, 0xbfb8aa3b, v88
	v_mul_f32_e32 v88, 0xbfb8aa3b, v89
	v_exp_f32_e32 v89, v88
	v_add_f32_e32 v87, 1.0, v87
	v_exp_f32_e32 v86, v84
	v_rcp_f32_e32 v88, v87
	v_add_f32_e32 v87, 1.0, v89
	v_mul_f32_e32 v89, 0xbfb8aa3b, v109
	v_exp_f32_e32 v89, v89
	v_add_f32_e32 v86, 1.0, v86
	v_rcp_f32_e32 v86, v86
	v_rcp_f32_e32 v87, v87
	v_add_f32_e32 v89, 1.0, v89
	v_add_f32_e32 v96, 1.0, v96
	v_rcp_f32_e32 v89, v89
	v_rcp_f32_e32 v96, v96
	s_waitcnt vmcnt(5)
	v_lshlrev_b32_e32 v114, 16, v214
	v_and_b32_e32 v115, 0xffff0000, v214
	v_lshlrev_b32_e32 v92, 16, v215
	v_and_b32_e32 v93, 0xffff0000, v215
	v_pk_mul_f32 v[82:83], v[94:95], v[114:115]
	v_pk_mul_f32 v[86:87], v[86:87], v[92:93]
	v_lshlrev_b32_e32 v92, 16, v217
	v_and_b32_e32 v93, 0xffff0000, v217
	v_lshlrev_b32_e32 v84, 16, v216
	v_and_b32_e32 v85, 0xffff0000, v216
	v_pk_mul_f32 v[88:89], v[88:89], v[92:93]
	v_pk_mul_f32 v[92:93], v[82:83], v[82:83]
	v_pk_mul_f32 v[94:95], v[86:87], v[86:87]
	v_pk_mul_f32 v[84:85], v[96:97], v[84:85]
	v_add_f32_e32 v94, v94, v95
	v_add_f32_e32 v92, v92, v93
	v_pk_mul_f32 v[96:97], v[84:85], v[84:85]
	v_add_f32_e32 v92, v92, v94
	v_add_f32_e32 v94, v102, v103
	v_add_f32_e32 v95, v100, v101
	v_pk_mul_f32 v[104:105], v[88:89], v[88:89]
	v_add_f32_e32 v93, v96, v97
	v_add_f32_e32 v94, v95, v94
	v_add_f32_e32 v95, v110, v111
	v_add_f32_e32 v104, v104, v105
	v_add_f32_e32 v92, v93, v92
	v_add_f32_e32 v93, v112, v113
	v_add_f32_e32 v94, v95, v94
	v_add_f32_e32 v92, v104, v92
	v_add_f32_e32 v93, v93, v94
	v_add_f32_e32 v94, v93, v92
	ds_bpermute_b32 v95, v189, v94
	v_pk_mul_f32 v[82:83], v[62:63], v[82:83]
	v_pk_mul_f32 v[92:93], v[58:59], v[84:85]
	v_cvt_pk_bf16_f32 v84, v82, v83
	v_pk_mul_f32 v[86:87], v[64:65], v[86:87]
	s_waitcnt lgkmcnt(0)
	v_add_f32_e32 v82, v94, v95
	ds_bpermute_b32 v83, v188, v82
	v_pk_mul_f32 v[88:89], v[60:61], v[88:89]
	v_cvt_pk_bf16_f32 v85, v86, v87
	v_cvt_pk_bf16_f32 v86, v92, v93
	v_cvt_pk_bf16_f32 v87, v88, v89
	global_store_dwordx4 v[90:91], v[84:87], off offset:256
	s_and_saveexec_b64 s[12:13], s[4:5]
	s_cbranch_execz .LBB0_476
	v_lshl_add_u64 v[84:85], v[98:99], 2, s[18:19]
	s_waitcnt lgkmcnt(0)
	v_add_f32_e32 v82, v82, v83
	global_atomic_add_f32 v[84:85], v82, off
.LBB0_476:
	s_or_b64 exec, exec, s[12:13]
	v_add_u32_e32 v82, 0x90, v180
	s_waitcnt lgkmcnt(0)
	v_ashrrev_i32_e32 v83, 31, v82
	v_lshlrev_b64 v[84:85], 11, v[82:83]
	v_lshl_add_u64 v[84:85], s[8:9], 0, v[84:85]
	v_lshl_add_u64 v[88:89], v[84:85], 0, v[178:179]
	v_add_u32_e32 v226, 160, v180
	v_ashrrev_i32_e32 v227, 31, v226
	v_lshlrev_b64 v[228:229], 11, v[226:227]
	v_lshl_add_u64 v[228:229], s[8:9], 0, v[228:229]
	v_lshl_add_u64 v[228:229], v[228:229], 0, v[178:179]
	global_load_dwordx4 v[210:213], v[228:229], off
	global_load_dwordx4 v[214:217], v[228:229], off offset:256
	v_pk_add_f32 v[48:49], v[48:49], v[72:73]
	v_pk_add_f32 v[46:47], v[46:47], v[70:71]
	v_pk_add_f32 v[44:45], v[44:45], v[68:69]
	v_pk_add_f32 v[42:43], v[42:43], v[66:67]
	v_pk_add_f32 v[38:39], v[38:39], v[74:75]
	v_pk_add_f32 v[92:93], v[36:37], v[80:81]
	v_mul_f32_e32 v36, 0xbfb8aa3b, v46
	v_mul_f32_e32 v37, 0xbfb8aa3b, v42
	v_mul_f32_e32 v42, 0xbfb8aa3b, v47
	v_mul_f32_e32 v43, 0xbfb8aa3b, v43
	v_mul_f32_e32 v46, 0xbfb8aa3b, v48
	v_mul_f32_e32 v44, 0xbfb8aa3b, v44
	v_mul_f32_e32 v47, 0xbfb8aa3b, v49
	v_mul_f32_e32 v45, 0xbfb8aa3b, v45
	v_mul_f32_e32 v38, 0xbfb8aa3b, v38
	v_mul_f32_e32 v39, 0xbfb8aa3b, v39
	v_exp_f32_e32 v36, v36
	v_exp_f32_e32 v37, v37
	v_exp_f32_e32 v94, v42
	v_exp_f32_e32 v95, v43
	v_exp_f32_e32 v46, v46
	v_exp_f32_e32 v44, v44
	v_exp_f32_e32 v47, v47
	v_exp_f32_e32 v45, v45
	v_pk_add_f32 v[34:35], v[34:35], v[78:79]
	v_exp_f32_e32 v38, v38
	v_exp_f32_e32 v39, v39
	v_mul_f32_e32 v48, 0xbfb8aa3b, v34
	v_mul_f32_e32 v49, 0xbfb8aa3b, v35
	v_lshlrev_b64 v[34:35], 12, v[82:83]
	v_lshl_add_u64 v[34:35], s[16:17], 0, v[34:35]
	v_lshl_add_u64 v[42:43], v[34:35], 0, v[178:179]
	v_add_f32_e32 v34, 1.0, v36
	v_add_f32_e32 v35, 1.0, v37
	v_add_f32_e32 v37, 1.0, v94
	v_add_f32_e32 v94, 1.0, v95
	v_add_f32_e32 v46, 1.0, v46
	v_add_f32_e32 v44, 1.0, v44
	v_add_f32_e32 v47, 1.0, v47
	v_add_f32_e32 v45, 1.0, v45
	v_add_f32_e32 v95, 1.0, v38
	v_add_f32_e32 v96, 1.0, v39
	v_rcp_f32_e32 v34, v34
	v_rcp_f32_e32 v36, v35
	v_rcp_f32_e32 v35, v37
	v_rcp_f32_e32 v37, v94
	v_rcp_f32_e32 v38, v46
	v_rcp_f32_e32 v44, v44
	v_rcp_f32_e32 v39, v47
	v_rcp_f32_e32 v45, v45
	v_exp_f32_e32 v49, v49
	v_rcp_f32_e32 v46, v95
	v_rcp_f32_e32 v47, v96
	v_pk_add_f32 v[40:41], v[40:41], v[76:77]
	v_exp_f32_e32 v48, v48
	s_waitcnt vmcnt(5)
	v_lshlrev_b32_e32 v94, 16, v218
	v_and_b32_e32 v95, 0xffff0000, v218
	v_lshlrev_b32_e32 v96, 16, v220
	v_and_b32_e32 v97, 0xffff0000, v220
	v_lshlrev_b32_e32 v84, 16, v219
	v_and_b32_e32 v85, 0xffff0000, v219
	v_lshlrev_b32_e32 v86, 16, v221
	v_and_b32_e32 v87, 0xffff0000, v221
	v_pk_mul_f32 v[34:35], v[34:35], v[94:95]
	v_pk_mul_f32 v[36:37], v[36:37], v[96:97]
	v_pk_mul_f32 v[38:39], v[38:39], v[84:85]
	v_pk_mul_f32 v[44:45], v[44:45], v[86:87]
	v_pk_mul_f32 v[84:85], v[34:35], v[34:35]
	v_pk_mul_f32 v[86:87], v[38:39], v[38:39]
	v_pk_mul_f32 v[94:95], v[36:37], v[36:37]
	v_pk_mul_f32 v[96:97], v[44:45], v[44:45]
	v_pk_mul_f32 v[38:39], v[56:57], v[38:39]
	v_pk_mul_f32 v[34:35], v[54:55], v[34:35]
	v_pk_mul_f32 v[44:45], v[52:53], v[44:45]
	v_pk_mul_f32 v[36:37], v[50:51], v[36:37]
	v_cvt_pk_bf16_f32 v34, v34, v35
	v_cvt_pk_bf16_f32 v35, v38, v39
	v_cvt_pk_bf16_f32 v36, v36, v37
	v_cvt_pk_bf16_f32 v37, v44, v45
	global_store_dwordx4 v[42:43], v[34:37], off
	v_mul_f32_e32 v39, 0xbfb8aa3b, v92
	v_exp_f32_e32 v39, v39
	v_add_f32_e32 v36, 1.0, v49
	v_rcp_f32_e32 v49, v36
	v_mul_f32_e32 v36, 0xbfb8aa3b, v40
	v_mul_f32_e32 v40, 0xbfb8aa3b, v41
	v_exp_f32_e32 v41, v40
	v_add_f32_e32 v39, 1.0, v39
	v_exp_f32_e32 v38, v36
	v_rcp_f32_e32 v40, v39
	v_add_f32_e32 v39, 1.0, v41
	v_mul_f32_e32 v41, 0xbfb8aa3b, v93
	v_exp_f32_e32 v41, v41
	v_add_f32_e32 v38, 1.0, v38
	v_rcp_f32_e32 v38, v38
	v_rcp_f32_e32 v39, v39
	v_add_f32_e32 v41, 1.0, v41
	v_add_f32_e32 v48, 1.0, v48
	v_rcp_f32_e32 v41, v41
	v_rcp_f32_e32 v48, v48
	s_waitcnt vmcnt(5)
	v_lshlrev_b32_e32 v98, 16, v222
	v_and_b32_e32 v99, 0xffff0000, v222
	v_lshlrev_b32_e32 v44, 16, v223
	v_and_b32_e32 v45, 0xffff0000, v223
	v_pk_mul_f32 v[34:35], v[46:47], v[98:99]
	v_pk_mul_f32 v[38:39], v[38:39], v[44:45]
	v_lshlrev_b32_e32 v44, 16, v225
	v_and_b32_e32 v45, 0xffff0000, v225
	v_lshlrev_b32_e32 v36, 16, v224
	v_and_b32_e32 v37, 0xffff0000, v224
	v_pk_mul_f32 v[40:41], v[40:41], v[44:45]
	v_pk_mul_f32 v[44:45], v[34:35], v[34:35]
	v_pk_mul_f32 v[46:47], v[38:39], v[38:39]
	v_pk_mul_f32 v[36:37], v[48:49], v[36:37]
	v_add_f32_e32 v46, v46, v47
	v_add_f32_e32 v44, v44, v45
	v_pk_mul_f32 v[48:49], v[36:37], v[36:37]
	v_add_f32_e32 v44, v44, v46
	v_add_f32_e32 v46, v86, v87
	v_add_f32_e32 v47, v84, v85
	v_pk_mul_f32 v[88:89], v[40:41], v[40:41]
	v_add_f32_e32 v45, v48, v49
	v_add_f32_e32 v46, v47, v46
	v_add_f32_e32 v47, v94, v95
	v_add_f32_e32 v88, v88, v89
	v_add_f32_e32 v44, v45, v44
	v_add_f32_e32 v45, v96, v97
	v_add_f32_e32 v46, v47, v46
	v_add_f32_e32 v44, v88, v44
	v_add_f32_e32 v45, v45, v46
	v_add_f32_e32 v46, v45, v44
	ds_bpermute_b32 v47, v189, v46
	v_pk_mul_f32 v[34:35], v[62:63], v[34:35]
	v_pk_mul_f32 v[44:45], v[58:59], v[36:37]
	v_cvt_pk_bf16_f32 v36, v34, v35
	v_pk_mul_f32 v[38:39], v[64:65], v[38:39]
	s_waitcnt lgkmcnt(0)
	v_add_f32_e32 v34, v46, v47
	ds_bpermute_b32 v35, v188, v34
	v_pk_mul_f32 v[40:41], v[60:61], v[40:41]
	v_cvt_pk_bf16_f32 v37, v38, v39
	v_cvt_pk_bf16_f32 v38, v44, v45
	v_cvt_pk_bf16_f32 v39, v40, v41
	global_store_dwordx4 v[42:43], v[36:39], off offset:256
	s_and_saveexec_b64 s[12:13], s[4:5]
	s_cbranch_execz .LBB0_478
	v_lshl_add_u64 v[36:37], v[82:83], 2, s[18:19]
	s_waitcnt lgkmcnt(0)
	v_add_f32_e32 v34, v34, v35
	global_atomic_add_f32 v[36:37], v34, off
.LBB0_478:
	s_or_b64 exec, exec, s[12:13]
	v_add_u32_e32 v34, 0xa0, v180
	s_waitcnt lgkmcnt(0)
	v_ashrrev_i32_e32 v35, 31, v34
	v_lshlrev_b64 v[36:37], 11, v[34:35]
	v_lshl_add_u64 v[36:37], s[8:9], 0, v[36:37]
	v_lshl_add_u64 v[40:41], v[36:37], 0, v[178:179]
	v_add_u32_e32 v226, 176, v180
	v_ashrrev_i32_e32 v227, 31, v226
	v_lshlrev_b64 v[228:229], 11, v[226:227]
	v_lshl_add_u64 v[228:229], s[8:9], 0, v[228:229]
	v_lshl_add_u64 v[228:229], v[228:229], 0, v[178:179]
	global_load_dwordx4 v[218:221], v[228:229], off
	global_load_dwordx4 v[222:225], v[228:229], off offset:256
	v_pk_add_f32 v[32:33], v[32:33], v[72:73]
	v_pk_add_f32 v[30:31], v[30:31], v[70:71]
	v_pk_add_f32 v[28:29], v[28:29], v[68:69]
	v_pk_add_f32 v[26:27], v[26:27], v[66:67]
	v_pk_add_f32 v[22:23], v[22:23], v[74:75]
	v_pk_add_f32 v[44:45], v[20:21], v[80:81]
	v_mul_f32_e32 v20, 0xbfb8aa3b, v30
	v_mul_f32_e32 v21, 0xbfb8aa3b, v26
	v_mul_f32_e32 v26, 0xbfb8aa3b, v31
	v_mul_f32_e32 v27, 0xbfb8aa3b, v27
	v_mul_f32_e32 v30, 0xbfb8aa3b, v32
	v_mul_f32_e32 v28, 0xbfb8aa3b, v28
	v_mul_f32_e32 v31, 0xbfb8aa3b, v33
	v_mul_f32_e32 v29, 0xbfb8aa3b, v29
	v_mul_f32_e32 v22, 0xbfb8aa3b, v22
	v_mul_f32_e32 v23, 0xbfb8aa3b, v23
	v_exp_f32_e32 v20, v20
	v_exp_f32_e32 v21, v21
	v_exp_f32_e32 v46, v26
	v_exp_f32_e32 v47, v27
	v_exp_f32_e32 v30, v30
	v_exp_f32_e32 v28, v28
	v_exp_f32_e32 v31, v31
	v_exp_f32_e32 v29, v29
	v_pk_add_f32 v[18:19], v[18:19], v[78:79]
	v_exp_f32_e32 v22, v22
	v_exp_f32_e32 v23, v23
	v_mul_f32_e32 v32, 0xbfb8aa3b, v18
	v_mul_f32_e32 v33, 0xbfb8aa3b, v19
	v_lshlrev_b64 v[18:19], 12, v[34:35]
	v_lshl_add_u64 v[18:19], s[16:17], 0, v[18:19]
	v_lshl_add_u64 v[26:27], v[18:19], 0, v[178:179]
	v_add_f32_e32 v18, 1.0, v20
	v_add_f32_e32 v19, 1.0, v21
	v_add_f32_e32 v21, 1.0, v46
	v_add_f32_e32 v46, 1.0, v47
	v_add_f32_e32 v30, 1.0, v30
	v_add_f32_e32 v28, 1.0, v28
	v_add_f32_e32 v31, 1.0, v31
	v_add_f32_e32 v29, 1.0, v29
	v_add_f32_e32 v47, 1.0, v22
	v_add_f32_e32 v48, 1.0, v23
	v_rcp_f32_e32 v18, v18
	v_rcp_f32_e32 v20, v19
	v_rcp_f32_e32 v19, v21
	v_rcp_f32_e32 v21, v46
	v_rcp_f32_e32 v22, v30
	v_rcp_f32_e32 v28, v28
	v_rcp_f32_e32 v23, v31
	v_rcp_f32_e32 v29, v29
	v_exp_f32_e32 v33, v33
	v_rcp_f32_e32 v30, v47
	v_rcp_f32_e32 v31, v48
	v_pk_add_f32 v[24:25], v[24:25], v[76:77]
	v_exp_f32_e32 v32, v32
	s_waitcnt vmcnt(5)
	v_lshlrev_b32_e32 v46, 16, v210
	v_and_b32_e32 v47, 0xffff0000, v210
	v_lshlrev_b32_e32 v48, 16, v212
	v_and_b32_e32 v49, 0xffff0000, v212
	v_lshlrev_b32_e32 v36, 16, v211
	v_and_b32_e32 v37, 0xffff0000, v211
	v_lshlrev_b32_e32 v38, 16, v213
	v_and_b32_e32 v39, 0xffff0000, v213
	v_pk_mul_f32 v[18:19], v[18:19], v[46:47]
	v_pk_mul_f32 v[20:21], v[20:21], v[48:49]
	v_pk_mul_f32 v[22:23], v[22:23], v[36:37]
	v_pk_mul_f32 v[28:29], v[28:29], v[38:39]
	v_pk_mul_f32 v[36:37], v[18:19], v[18:19]
	v_pk_mul_f32 v[38:39], v[22:23], v[22:23]
	v_pk_mul_f32 v[46:47], v[20:21], v[20:21]
	v_pk_mul_f32 v[48:49], v[28:29], v[28:29]
	v_pk_mul_f32 v[22:23], v[56:57], v[22:23]
	v_pk_mul_f32 v[18:19], v[54:55], v[18:19]
	v_pk_mul_f32 v[28:29], v[52:53], v[28:29]
	v_pk_mul_f32 v[20:21], v[50:51], v[20:21]
	v_cvt_pk_bf16_f32 v18, v18, v19
	v_cvt_pk_bf16_f32 v19, v22, v23
	v_cvt_pk_bf16_f32 v20, v20, v21
	v_cvt_pk_bf16_f32 v21, v28, v29
	global_store_dwordx4 v[26:27], v[18:21], off
	v_mul_f32_e32 v23, 0xbfb8aa3b, v44
	v_exp_f32_e32 v23, v23
	v_add_f32_e32 v20, 1.0, v33
	v_rcp_f32_e32 v33, v20
	v_mul_f32_e32 v20, 0xbfb8aa3b, v24
	v_mul_f32_e32 v24, 0xbfb8aa3b, v25
	v_exp_f32_e32 v25, v24
	v_add_f32_e32 v23, 1.0, v23
	v_exp_f32_e32 v22, v20
	v_rcp_f32_e32 v24, v23
	v_add_f32_e32 v23, 1.0, v25
	v_mul_f32_e32 v25, 0xbfb8aa3b, v45
	v_exp_f32_e32 v25, v25
	v_add_f32_e32 v22, 1.0, v22
	v_rcp_f32_e32 v22, v22
	v_rcp_f32_e32 v23, v23
	v_add_f32_e32 v25, 1.0, v25
	v_add_f32_e32 v32, 1.0, v32
	v_rcp_f32_e32 v25, v25
	v_rcp_f32_e32 v32, v32
	s_waitcnt vmcnt(5)
	v_lshlrev_b32_e32 v82, 16, v214
	v_and_b32_e32 v83, 0xffff0000, v214
	v_lshlrev_b32_e32 v28, 16, v215
	v_and_b32_e32 v29, 0xffff0000, v215
	v_pk_mul_f32 v[18:19], v[30:31], v[82:83]
	v_pk_mul_f32 v[22:23], v[22:23], v[28:29]
	v_lshlrev_b32_e32 v28, 16, v217
	v_and_b32_e32 v29, 0xffff0000, v217
	v_lshlrev_b32_e32 v20, 16, v216
	v_and_b32_e32 v21, 0xffff0000, v216
	v_pk_mul_f32 v[24:25], v[24:25], v[28:29]
	v_pk_mul_f32 v[28:29], v[18:19], v[18:19]
	v_pk_mul_f32 v[30:31], v[22:23], v[22:23]
	v_pk_mul_f32 v[20:21], v[32:33], v[20:21]
	v_add_f32_e32 v30, v30, v31
	v_add_f32_e32 v28, v28, v29
	v_pk_mul_f32 v[32:33], v[20:21], v[20:21]
	v_add_f32_e32 v28, v28, v30
	v_add_f32_e32 v30, v38, v39
	v_add_f32_e32 v31, v36, v37
	v_pk_mul_f32 v[40:41], v[24:25], v[24:25]
	v_add_f32_e32 v29, v32, v33
	v_add_f32_e32 v30, v31, v30
	v_add_f32_e32 v31, v46, v47
	v_add_f32_e32 v40, v40, v41
	v_add_f32_e32 v28, v29, v28
	v_add_f32_e32 v29, v48, v49
	v_add_f32_e32 v30, v31, v30
	v_add_f32_e32 v28, v40, v28
	v_add_f32_e32 v29, v29, v30
	v_add_f32_e32 v30, v29, v28
	ds_bpermute_b32 v31, v189, v30
	v_pk_mul_f32 v[18:19], v[62:63], v[18:19]
	v_pk_mul_f32 v[28:29], v[58:59], v[20:21]
	v_cvt_pk_bf16_f32 v20, v18, v19
	v_pk_mul_f32 v[22:23], v[64:65], v[22:23]
	s_waitcnt lgkmcnt(0)
	v_add_f32_e32 v18, v30, v31
	ds_bpermute_b32 v19, v188, v18
	v_pk_mul_f32 v[24:25], v[60:61], v[24:25]
	v_cvt_pk_bf16_f32 v21, v22, v23
	v_cvt_pk_bf16_f32 v22, v28, v29
	v_cvt_pk_bf16_f32 v23, v24, v25
	global_store_dwordx4 v[26:27], v[20:23], off offset:256
	s_and_saveexec_b64 s[12:13], s[4:5]
	s_cbranch_execz .LBB0_480
	v_lshl_add_u64 v[20:21], v[34:35], 2, s[18:19]
	s_waitcnt lgkmcnt(0)
	v_add_f32_e32 v18, v18, v19
	global_atomic_add_f32 v[20:21], v18, off
.LBB0_480:
	s_or_b64 exec, exec, s[12:13]
	v_add_u32_e32 v18, 0xb0, v180
	s_waitcnt lgkmcnt(0)
	v_ashrrev_i32_e32 v19, 31, v18
	v_lshlrev_b64 v[20:21], 11, v[18:19]
	v_lshl_add_u64 v[20:21], s[8:9], 0, v[20:21]
	v_lshl_add_u64 v[24:25], v[20:21], 0, v[178:179]
	v_pk_add_f32 v[16:17], v[16:17], v[72:73]
	v_pk_add_f32 v[14:15], v[14:15], v[70:71]
	v_pk_add_f32 v[12:13], v[12:13], v[68:69]
	v_pk_add_f32 v[10:11], v[10:11], v[66:67]
	v_pk_add_f32 v[6:7], v[6:7], v[74:75]
	v_pk_add_f32 v[28:29], v[4:5], v[80:81]
	v_mul_f32_e32 v4, 0xbfb8aa3b, v14
	v_mul_f32_e32 v5, 0xbfb8aa3b, v10
	v_mul_f32_e32 v10, 0xbfb8aa3b, v15
	v_mul_f32_e32 v11, 0xbfb8aa3b, v11
	v_mul_f32_e32 v14, 0xbfb8aa3b, v16
	v_mul_f32_e32 v12, 0xbfb8aa3b, v12
	v_mul_f32_e32 v15, 0xbfb8aa3b, v17
	v_mul_f32_e32 v13, 0xbfb8aa3b, v13
	v_mul_f32_e32 v6, 0xbfb8aa3b, v6
	v_mul_f32_e32 v7, 0xbfb8aa3b, v7
	v_exp_f32_e32 v4, v4
	v_exp_f32_e32 v5, v5
	v_exp_f32_e32 v30, v10
	v_exp_f32_e32 v31, v11
	v_exp_f32_e32 v14, v14
	v_exp_f32_e32 v12, v12
	v_exp_f32_e32 v15, v15
	v_exp_f32_e32 v13, v13
	v_pk_add_f32 v[2:3], v[2:3], v[78:79]
	v_exp_f32_e32 v6, v6
	v_exp_f32_e32 v7, v7
	v_mul_f32_e32 v16, 0xbfb8aa3b, v2
	v_mul_f32_e32 v17, 0xbfb8aa3b, v3
	v_lshlrev_b64 v[2:3], 12, v[18:19]
	v_lshl_add_u64 v[2:3], s[16:17], 0, v[2:3]
	v_lshl_add_u64 v[10:11], v[2:3], 0, v[178:179]
	v_add_f32_e32 v2, 1.0, v4
	v_add_f32_e32 v3, 1.0, v5
	v_add_f32_e32 v5, 1.0, v30
	v_add_f32_e32 v30, 1.0, v31
	v_add_f32_e32 v14, 1.0, v14
	v_add_f32_e32 v12, 1.0, v12
	v_add_f32_e32 v15, 1.0, v15
	v_add_f32_e32 v13, 1.0, v13
	v_add_f32_e32 v31, 1.0, v6
	v_add_f32_e32 v32, 1.0, v7
	v_rcp_f32_e32 v2, v2
	v_rcp_f32_e32 v4, v3
	v_rcp_f32_e32 v3, v5
	v_rcp_f32_e32 v5, v30
	v_rcp_f32_e32 v6, v14
	v_rcp_f32_e32 v12, v12
	v_rcp_f32_e32 v7, v15
	v_rcp_f32_e32 v13, v13
	v_exp_f32_e32 v17, v17
	v_rcp_f32_e32 v14, v31
	v_rcp_f32_e32 v15, v32
	v_pk_add_f32 v[8:9], v[8:9], v[76:77]
	v_exp_f32_e32 v16, v16
	s_waitcnt vmcnt(3)
	v_lshlrev_b32_e32 v30, 16, v218
	v_and_b32_e32 v31, 0xffff0000, v218
	v_lshlrev_b32_e32 v32, 16, v220
	v_and_b32_e32 v33, 0xffff0000, v220
	v_lshlrev_b32_e32 v20, 16, v219
	v_and_b32_e32 v21, 0xffff0000, v219
	v_lshlrev_b32_e32 v22, 16, v221
	v_and_b32_e32 v23, 0xffff0000, v221
	v_pk_mul_f32 v[2:3], v[2:3], v[30:31]
	v_pk_mul_f32 v[4:5], v[4:5], v[32:33]
	v_pk_mul_f32 v[6:7], v[6:7], v[20:21]
	v_pk_mul_f32 v[12:13], v[12:13], v[22:23]
	v_pk_mul_f32 v[20:21], v[2:3], v[2:3]
	v_pk_mul_f32 v[22:23], v[6:7], v[6:7]
	v_pk_mul_f32 v[30:31], v[4:5], v[4:5]
	v_pk_mul_f32 v[32:33], v[12:13], v[12:13]
	v_pk_mul_f32 v[6:7], v[56:57], v[6:7]
	v_pk_mul_f32 v[2:3], v[54:55], v[2:3]
	v_pk_mul_f32 v[12:13], v[52:53], v[12:13]
	v_pk_mul_f32 v[4:5], v[50:51], v[4:5]
	v_cvt_pk_bf16_f32 v2, v2, v3
	v_cvt_pk_bf16_f32 v3, v6, v7
	v_cvt_pk_bf16_f32 v4, v4, v5
	v_cvt_pk_bf16_f32 v5, v12, v13
	global_store_dwordx4 v[10:11], v[2:5], off
	v_mul_f32_e32 v7, 0xbfb8aa3b, v28
	v_exp_f32_e32 v7, v7
	v_add_f32_e32 v4, 1.0, v17
	v_rcp_f32_e32 v17, v4
	v_mul_f32_e32 v4, 0xbfb8aa3b, v8
	v_mul_f32_e32 v8, 0xbfb8aa3b, v9
	v_exp_f32_e32 v9, v8
	v_add_f32_e32 v7, 1.0, v7
	v_exp_f32_e32 v6, v4
	v_rcp_f32_e32 v8, v7
	v_add_f32_e32 v7, 1.0, v9
	v_mul_f32_e32 v9, 0xbfb8aa3b, v29
	v_exp_f32_e32 v9, v9
	v_add_f32_e32 v6, 1.0, v6
	v_rcp_f32_e32 v6, v6
	v_rcp_f32_e32 v7, v7
	v_add_f32_e32 v9, 1.0, v9
	v_add_f32_e32 v16, 1.0, v16
	v_rcp_f32_e32 v9, v9
	v_rcp_f32_e32 v16, v16
	s_waitcnt vmcnt(3)
	v_lshlrev_b32_e32 v34, 16, v222
	v_and_b32_e32 v35, 0xffff0000, v222
	v_lshlrev_b32_e32 v12, 16, v223
	v_and_b32_e32 v13, 0xffff0000, v223
	v_pk_mul_f32 v[2:3], v[14:15], v[34:35]
	v_pk_mul_f32 v[6:7], v[6:7], v[12:13]
	v_lshlrev_b32_e32 v12, 16, v225
	v_and_b32_e32 v13, 0xffff0000, v225
	v_lshlrev_b32_e32 v4, 16, v224
	v_and_b32_e32 v5, 0xffff0000, v224
	v_pk_mul_f32 v[8:9], v[8:9], v[12:13]
	v_pk_mul_f32 v[12:13], v[2:3], v[2:3]
	v_pk_mul_f32 v[14:15], v[6:7], v[6:7]
	v_pk_mul_f32 v[4:5], v[16:17], v[4:5]
	v_add_f32_e32 v14, v14, v15
	v_add_f32_e32 v12, v12, v13
	v_pk_mul_f32 v[16:17], v[4:5], v[4:5]
	v_add_f32_e32 v12, v12, v14
	v_add_f32_e32 v14, v22, v23
	v_add_f32_e32 v15, v20, v21
	v_pk_mul_f32 v[24:25], v[8:9], v[8:9]
	v_add_f32_e32 v13, v16, v17
	v_add_f32_e32 v14, v15, v14
	v_add_f32_e32 v15, v30, v31
	v_add_f32_e32 v24, v24, v25
	v_add_f32_e32 v12, v13, v12
	v_add_f32_e32 v13, v32, v33
	v_add_f32_e32 v14, v15, v14
	v_add_f32_e32 v12, v24, v12
	v_add_f32_e32 v13, v13, v14
	v_add_f32_e32 v14, v13, v12
	ds_bpermute_b32 v15, v189, v14
	v_pk_mul_f32 v[2:3], v[62:63], v[2:3]
	v_pk_mul_f32 v[12:13], v[58:59], v[4:5]
	v_cvt_pk_bf16_f32 v4, v2, v3
	v_pk_mul_f32 v[6:7], v[64:65], v[6:7]
	s_waitcnt lgkmcnt(0)
	v_add_f32_e32 v2, v14, v15
	ds_bpermute_b32 v3, v188, v2
	v_pk_mul_f32 v[8:9], v[60:61], v[8:9]
	v_cvt_pk_bf16_f32 v5, v6, v7
	v_cvt_pk_bf16_f32 v6, v12, v13
	v_cvt_pk_bf16_f32 v7, v8, v9
	global_store_dwordx4 v[10:11], v[4:7], off offset:256
	s_and_saveexec_b64 s[12:13], s[4:5]
	s_cbranch_execz .LBB0_482
	v_lshl_add_u64 v[4:5], v[18:19], 2, s[18:19]
	s_waitcnt lgkmcnt(0)
	v_add_f32_e32 v2, v2, v3
	global_atomic_add_f32 v[4:5], v2, off
